# replace 14 of 17 cooperative-groups grid syncs by a flat counter barrier in ws (release wbl2 + atomic arrive + sc1 poll + inv)
# speedup vs baseline: 1.0133x; 1.0133x over previous
; __global__ void __launch_bounds__(512, 2) hybrid_fwd(Params P) {
;     ...
;         grid.sync();
.LBB0_730:
	s_waitcnt vmcnt(0)
	s_barrier
	s_mov_b64 s[4:5], exec
	v_readlane_b32 s6, v255, 5
	v_readlane_b32 s7, v255, 6
	s_and_b64 s[6:7], s[4:5], s[6:7]
	v_readlane_b32 s27, v255, 0
	s_movk_i32 s29, 0x204
	s_movk_i32 s34, 0x1f8
	s_movk_i32 s35, 0x7e
	s_mov_b64 s[36:37], 0x800
	s_mov_b64 exec, s[6:7]
	s_cbranch_execz .LBB0_740
	buffer_wbl2 sc1
	s_waitcnt vmcnt(0)
	v_readlane_b32 s8, v255, 17
	v_mov_b32_e32 v1, 0
	v_mov_b32_e32 v0, 1
	s_lshl_b32 s8, s8, 5
	s_add_u32 s6, s58, s8
	s_addc_u32 s7, s59, 0
	s_mov_b32 s10, 0
	global_atomic_add v1, v0, s[6:7] offset:68
.Lgb_poll_1:
	global_load_dword v2, v1, s[6:7] offset:68 sc1
	s_waitcnt vmcnt(0)
	v_readfirstlane_b32 s8, v2
	s_cmp_ge_u32 s8, s69
	s_cbranch_scc1 .Lgb_done_1
	s_add_u32 s10, s10, 1
	s_cmp_gt_u32 s10, 0x40000
	s_cbranch_scc1 .Lgb_done_1
	s_sleep 1
	s_branch .Lgb_poll_1
.Lgb_done_1:
	buffer_inv sc1
	s_waitcnt vmcnt(0)

; __global__ void __launch_bounds__(512, 2) hybrid_fwd(Params P) {
;     ...
;         grid.sync();
.LBB0_767:
	s_waitcnt vmcnt(0)
	s_barrier
	s_mov_b64 s[4:5], exec
	v_readlane_b32 s6, v255, 5
	v_readlane_b32 s7, v255, 6
	s_and_b64 s[6:7], s[4:5], s[6:7]
	s_mov_b64 exec, s[6:7]
	s_cbranch_execz .LBB0_777
	buffer_wbl2 sc1
	s_waitcnt vmcnt(0)
	v_readlane_b32 s8, v255, 17
	v_mov_b32_e32 v1, 0
	v_mov_b32_e32 v0, 1
	s_lshl_b32 s8, s8, 5
	s_add_u32 s6, s58, s8
	s_addc_u32 s7, s59, 0
	s_mov_b32 s10, 0
	global_atomic_add v1, v0, s[6:7] offset:72
.Lgb_poll_2:
	global_load_dword v2, v1, s[6:7] offset:72 sc1
	s_waitcnt vmcnt(0)
	v_readfirstlane_b32 s8, v2
	s_cmp_ge_u32 s8, s69
	s_cbranch_scc1 .Lgb_done_2
	s_add_u32 s10, s10, 1
	s_cmp_gt_u32 s10, 0x40000
	s_cbranch_scc1 .Lgb_done_2
	s_sleep 1
	s_branch .Lgb_poll_2

; __global__ void __launch_bounds__(512, 2) hybrid_fwd(Params P) {
;     ...
;         grid.sync();
.LBB0_784:
	s_waitcnt vmcnt(0)
	s_barrier
	s_mov_b64 s[4:5], exec
	v_readlane_b32 s6, v255, 5
	v_readlane_b32 s7, v255, 6
	s_and_b64 s[6:7], s[4:5], s[6:7]
	s_mov_b64 exec, s[6:7]
	s_cbranch_execz .LBB0_794
	buffer_wbl2 sc1
	s_waitcnt vmcnt(0)
	v_readlane_b32 s8, v255, 17
	v_mov_b32_e32 v1, 0
	v_mov_b32_e32 v0, 1
	s_lshl_b32 s8, s8, 5
	s_add_u32 s6, s58, s8
	s_addc_u32 s7, s59, 0
	s_mov_b32 s10, 0
	global_atomic_add v1, v0, s[6:7] offset:76
.Lgb_poll_3:
	global_load_dword v2, v1, s[6:7] offset:76 sc1
	s_waitcnt vmcnt(0)
	v_readfirstlane_b32 s8, v2
	s_cmp_ge_u32 s8, s69
	s_cbranch_scc1 .Lgb_done_3
	s_add_u32 s10, s10, 1
	s_cmp_gt_u32 s10, 0x40000
	s_cbranch_scc1 .Lgb_done_3
	s_sleep 1
	s_branch .Lgb_poll_3

; __global__ void __launch_bounds__(512, 2) hybrid_fwd(Params P) {
;     ...
;         grid.sync();
.LBB0_1075:
	s_waitcnt vmcnt(0)
	s_barrier
	s_mov_b64 s[4:5], exec
	v_readlane_b32 s6, v255, 5
	v_readlane_b32 s7, v255, 6
	s_and_b64 s[6:7], s[4:5], s[6:7]
	v_readlane_b32 s34, v255, 17
	s_mov_b64 exec, s[6:7]
	s_cbranch_execz .LBB0_1085
	buffer_wbl2 sc1
	s_waitcnt vmcnt(0)
	v_readlane_b32 s8, v255, 17
	v_mov_b32_e32 v1, 0
	v_mov_b32_e32 v0, 1
	s_lshl_b32 s8, s8, 5
	s_add_u32 s6, s58, s8
	s_addc_u32 s7, s59, 0
	s_mov_b32 s10, 0
	global_atomic_add v1, v0, s[6:7] offset:80
.Lgb_poll_4:
	global_load_dword v2, v1, s[6:7] offset:80 sc1
	s_waitcnt vmcnt(0)
	v_readfirstlane_b32 s8, v2
	s_cmp_ge_u32 s8, s69
	s_cbranch_scc1 .Lgb_done_4
	s_add_u32 s10, s10, 1
	s_cmp_gt_u32 s10, 0x40000
	s_cbranch_scc1 .Lgb_done_4
	s_sleep 1
	s_branch .Lgb_poll_4

; __global__ void __launch_bounds__(512, 2) hybrid_fwd(Params P) {
;     ...
;         grid.sync();
.LBB0_1096:
	s_waitcnt vmcnt(0)
	s_barrier
	s_mov_b64 s[4:5], exec
	v_readlane_b32 s6, v255, 5
	v_readlane_b32 s7, v255, 6
	s_and_b64 s[6:7], s[4:5], s[6:7]
	s_mov_b64 exec, s[6:7]
	s_cbranch_execz .LBB0_1106
	buffer_wbl2 sc1
	s_waitcnt vmcnt(0)
	v_readlane_b32 s8, v255, 17
	v_mov_b32_e32 v1, 0
	v_mov_b32_e32 v0, 1
	s_lshl_b32 s8, s8, 5
	s_add_u32 s6, s58, s8
	s_addc_u32 s7, s59, 0
	s_mov_b32 s10, 0
	global_atomic_add v1, v0, s[6:7] offset:84
.Lgb_poll_5:
	global_load_dword v2, v1, s[6:7] offset:84 sc1
	s_waitcnt vmcnt(0)
	v_readfirstlane_b32 s8, v2
	s_cmp_ge_u32 s8, s69
	s_cbranch_scc1 .Lgb_done_5
	s_add_u32 s10, s10, 1
	s_cmp_gt_u32 s10, 0x40000
	s_cbranch_scc1 .Lgb_done_5
	s_sleep 1
	s_branch .Lgb_poll_5

; __global__ void __launch_bounds__(512, 2) hybrid_fwd(Params P) {
;     ...
;         grid.sync();
.LBB0_1193:
	s_waitcnt lgkmcnt(0)
	s_waitcnt vmcnt(0)
	s_barrier
	s_mov_b64 s[4:5], exec
	v_readlane_b32 s6, v255, 5
	v_readlane_b32 s7, v255, 6
	s_and_b64 s[6:7], s[4:5], s[6:7]
	s_mov_b64 s[36:37], 0x800
	s_mov_b64 exec, s[6:7]
	s_cbranch_execz .LBB0_1203
	buffer_wbl2 sc1
	s_waitcnt vmcnt(0)
	v_readlane_b32 s8, v255, 17
	v_mov_b32_e32 v1, 0
	v_mov_b32_e32 v0, 1
	s_lshl_b32 s8, s8, 5
	s_add_u32 s6, s58, s8
	s_addc_u32 s7, s59, 0
	s_mov_b32 s10, 0
	global_atomic_add v1, v0, s[6:7] offset:88
.Lgb_poll_6:
	global_load_dword v2, v1, s[6:7] offset:88 sc1
	s_waitcnt vmcnt(0)
	v_readfirstlane_b32 s8, v2
	s_cmp_ge_u32 s8, s69
	s_cbranch_scc1 .Lgb_done_6
	s_add_u32 s10, s10, 1
	s_cmp_gt_u32 s10, 0x40000
	s_cbranch_scc1 .Lgb_done_6
	s_sleep 1
	s_branch .Lgb_poll_6

; __global__ void __launch_bounds__(512, 2) hybrid_fwd(Params P) {
;     ...
;         grid.sync();
.LBB0_1219:
	s_waitcnt vmcnt(0)
	s_barrier
	s_mov_b64 s[4:5], exec
	v_readlane_b32 s6, v255, 5
	v_readlane_b32 s7, v255, 6
	s_and_b64 s[6:7], s[4:5], s[6:7]
	s_mov_b64 exec, s[6:7]
	s_cbranch_execz .LBB0_1229
	buffer_wbl2 sc1
	s_waitcnt vmcnt(0)
	v_readlane_b32 s8, v255, 17
	v_mov_b32_e32 v1, 0
	v_mov_b32_e32 v0, 1
	s_lshl_b32 s8, s8, 5
	s_add_u32 s6, s58, s8
	s_addc_u32 s7, s59, 0
	s_mov_b32 s10, 0
	global_atomic_add v1, v0, s[6:7] offset:92
.Lgb_poll_7:
	global_load_dword v2, v1, s[6:7] offset:92 sc1
	s_waitcnt vmcnt(0)
	v_readfirstlane_b32 s8, v2
	s_cmp_ge_u32 s8, s69
	s_cbranch_scc1 .Lgb_done_7
	s_add_u32 s10, s10, 1
	s_cmp_gt_u32 s10, 0x40000
	s_cbranch_scc1 .Lgb_done_7
	s_sleep 1
	s_branch .Lgb_poll_7
